# odd workgroups start the banded attention units ~8.7 us later (their tile-load bursts interleave with the even workgroups' compute)
# baseline (speedup 1.0000x reference)
.LBB0_494:
	s_bitcmp1_b32 s73, 0
	s_cbranch_scc0 .Lstg_att
	s_sleep 127
	s_sleep 127
